# NSA block loops: lane-linear coalesced K/V block loads + remapped LDS staging writes
# speedup vs baseline: 1.0153x; 1.0153x over previous
.LBB0_1464:
	s_or_b64 exec, exec, s[0:1]
	s_andn2_b64 vcc, exec, s[18:19]
	s_waitcnt lgkmcnt(0)
	s_barrier
	s_cbranch_vccnz .LBB0_1682
	s_mov_b32 s98, 0x2000
	s_mov_b32 s99, 0
	v_lshrrev_b32_e32 v244, 4, v220
	v_and_b32_e32 v245, 3, v244
	v_lshrrev_b32_e32 v246, 7, v220
	v_lshl_or_b32 v245, v246, 2, v245
	v_and_b32_e32 v246, 15, v220
	v_xor_b32_e32 v245, v245, v246
	v_lshlrev_b32_e32 v245, 4, v245
	v_lshl_or_b32 v249, v244, 8, v245
	v_xor_b32_e32 v250, 0x80, v249
	v_and_b32_e32 v245, 7, v244
	v_and_b32_e32 v246, 7, v220
	v_xor_b32_e32 v245, v245, v246
	v_lshlrev_b32_e32 v245, 4, v245
	v_lshrrev_b32_e32 v246, 3, v220
	v_lshl_or_b32 v251, v246, 7, v245
	v_lshlrev_b32_e32 v252, 4, v220
	v_add_u32_e32 v252, 0x1000, v252
	v_mov_b32_e32 v253, 0
	s_mov_b32 s57, 0
	s_cmpk_lg_i32 s74, 0x200
	s_mov_b32 s3, s57
	s_cselect_b64 s[52:53], -1, 0
	s_lshr_b32 s0, s2, 8
	s_lshl_b64 s[58:59], s[2:3], 8
	s_add_u32 s60, s72, 0x13200000
	s_addc_u32 s61, s73, 0
	s_add_u32 s62, s72, 0x3000000
	s_addc_u32 s63, s73, 0
	s_add_u32 s3, s72, 0x3600000
	s_addc_u32 s87, s73, 0
	s_add_u32 s88, s72, 0x3800000
	s_addc_u32 s89, s73, 0
	s_add_u32 s64, s72, 0x7200000
	s_addc_u32 s65, s73, 0
	s_add_u32 s90, s72, 0xb200000
	s_addc_u32 s91, s73, 0
	v_writelane_b32 v254, s54, 32
	s_add_u32 s92, s72, 0xd200000
	s_addc_u32 s93, s73, 0
	v_writelane_b32 v254, s55, 33
	v_writelane_b32 v254, s0, 24
	s_add_u32 s0, s72, 0x11200000
	v_writelane_b32 v254, s0, 22
	s_addc_u32 s0, s73, 0
	s_add_u32 s96, s72, 0xf200000
	s_addc_u32 s97, s73, 0
	s_movk_i32 s4, 0x1ff
	s_waitcnt vmcnt(15)
	v_mov_b32_e32 v168, 0x10200
	v_mov_b32_e32 v17, 0
	s_mov_b32 s5, 0x8000
	s_movk_i32 s8, 0x400
	s_movk_i32 s9, 0x7fff
	v_mov_b32_e32 v169, 0xf149f2ca
	v_mbcnt_hi_u32_b32 v170, -1, v221
	v_mov_b32_e32 v171, 0xc0
	v_mov_b32_e32 v172, 0x7149f200
	v_mov_b32_e32 v173, 0x7149f2ca
	v_mov_b32_e32 v174, 1
	s_mov_b32 s6, s2
	v_writelane_b32 v254, s0, 26
	s_branch .LBB0_1468

.LBB0_1473:
	v_add_u32_e32 v3, 64, v3
	s_movk_i32 s7, 0x7df
	v_cmp_lt_u32_e32 vcc, s7, v3
	ds_write_b32 v2, v17
	s_or_b64 s[0:1], vcc, s[0:1]
	v_add_u32_e32 v2, 0x100, v2
	s_andn2_b64 exec, exec, s[0:1]
	s_cbranch_execnz .LBB0_1473
	s_or_b64 exec, exec, s[0:1]
	s_lshl_b32 s0, s66, 2
	s_and_b32 s7, s0, 12
	s_lshl_b32 s0, s66, 12
	s_lshl_b32 s77, s50, 5
	s_and_b32 s76, s0, 0xffffc000
	s_add_i32 s76, s76, s77
	v_lshlrev_b32_e32 v156, 3, v1
	v_and_or_b32 v3, v0, 3, s7
	v_add_u32_e32 v1, s76, v156
	v_lshrrev_b32_e32 v2, 2, v0
	v_and_or_b32 v2, v2, 3, v1
	v_lshlrev_b32_e32 v16, 8, v3
	v_lshl_add_u64 v[4:5], s[60:61], 0, v[16:17]
	v_and_b32_e32 v16, 48, v0
	v_ashrrev_i32_e32 v3, 31, v2
	v_lshl_add_u64 v[0:1], v[4:5], 0, v[16:17]
	v_lshlrev_b64 v[4:5], 12, v[2:3]
	v_or_b32_e32 v2, 4, v2
	v_ashrrev_i32_e32 v3, 31, v2
	v_lshlrev_b64 v[2:3], 12, v[2:3]
	v_lshl_add_u64 v[4:5], v[0:1], 0, v[4:5]
	v_lshl_add_u64 v[0:1], v[0:1], 0, v[2:3]
	s_waitcnt lgkmcnt(0)
	s_barrier
	global_load_dwordx4 v[20:23], v[4:5], off
	global_load_dwordx4 v[24:27], v[4:5], off offset:64
	global_load_dwordx4 v[28:31], v[4:5], off offset:128
	global_load_dwordx4 v[32:35], v[4:5], off offset:192
	global_load_dwordx4 v[36:39], v[0:1], off
	global_load_dwordx4 v[40:43], v[0:1], off offset:64
	global_load_dwordx4 v[44:47], v[0:1], off offset:128
	global_load_dwordx4 v[48:51], v[0:1], off offset:192
	s_lshl_b32 s0, s50, 1
	s_or_b32 s0, s0, 1
	s_ashr_i32 s67, s66, 31
	s_max_i32 s16, s0, 0
	s_lshl_b64 s[10:11], s[66:67], 18
	s_add_u32 s0, s3, s10
	s_addc_u32 s1, s87, s11
	s_add_u32 s14, s88, s10
	s_addc_u32 s15, s89, s11
	v_mov_b32_e32 v2, v220
	s_cmp_lg_u32 s16, 0
	s_cselect_b64 s[12:13], -1, 0
	v_lshlrev_b32_e32 v0, 5, v2
	s_and_b64 vcc, exec, s[12:13]
	v_ashrrev_i32_e32 v1, 31, v0
	s_cbranch_vccz .LBB0_1476
	v_mov_b64_e32 v[4:5], v[252:253]
	v_lshl_add_u64 v[6:7], s[0:1], 0, v[4:5]
	v_lshl_add_u64 v[4:5], s[14:15], 0, v[4:5]
	v_lshl_add_u64 v[246:247], v[6:7], 0, s[98:99]
	global_load_dwordx4 v[116:119], v[246:247], off
	global_load_dwordx4 v[120:123], v[246:247], off offset:-4096
	global_load_dwordx4 v[124:127], v[6:7], off
	global_load_dwordx4 v[128:131], v[6:7], off offset:-4096
	v_lshl_add_u64 v[244:245], v[4:5], 0, s[98:99]
	global_load_dwordx4 v[132:135], v[244:245], off
	global_load_dwordx4 v[136:139], v[244:245], off offset:-4096
	global_load_dwordx4 v[140:143], v[4:5], off
	global_load_dwordx4 v[144:147], v[4:5], off offset:-4096
.LBB0_1476:
	s_add_i32 s10, s16, 63
	s_lshr_b32 s51, s10, 6
	s_add_i32 s51, s51, -1
	s_cmp_lg_u32 s16, 0
	s_cselect_b64 s[10:11], -1, 0
	s_cmp_eq_u32 s16, 0
	s_cbranch_scc1 .LBB0_1500
	v_lshrrev_b32_e32 v7, 3, v2
	v_ashrrev_i32_e32 v6, 2, v2
	v_and_b32_e32 v7, 12, v7
	v_lshlrev_b32_e32 v9, 2, v2
	v_and_or_b32 v7, v6, 3, v7
	v_lshlrev_b32_e32 v6, 4, v6
	v_and_b32_e32 v10, 12, v9
	v_bitop3_b32 v11, v7, v6, v10 bitop3:0xde
	v_lshlrev_b32_e32 v161, 4, v11
	v_or_b32_e32 v11, 1, v10
	v_bitop3_b32 v11, v11, v6, v7 bitop3:0xde
	v_lshlrev_b32_e32 v162, 4, v11
	v_or_b32_e32 v11, 2, v10
	v_or_b32_e32 v10, 3, v10
	v_bfe_u32 v8, v2, 2, 3
	v_bitop3_b32 v11, v11, v6, v7 bitop3:0xde
	v_bitop3_b32 v6, v10, v6, v7 bitop3:0xde
	v_lshlrev_b32_e32 v164, 4, v6
	v_and_b32_e32 v6, -8, v9
	v_and_b32_e32 v7, 4, v9
	v_bitop3_b32 v9, v9, v8, 4 bitop3:0x6c
	v_or_b32_e32 v9, v9, v6
	v_lshlrev_b32_e32 v165, 4, v9
	v_bitop3_b32 v9, v7, v8, 1 bitop3:0x36
	v_or_b32_e32 v9, v9, v6
	v_lshlrev_b32_e32 v166, 4, v9
	v_bitop3_b32 v9, v7, v8, 2 bitop3:0x36
	v_bitop3_b32 v7, v7, v8, 3 bitop3:0x36
	v_and_b32_e32 v3, 15, v2
	v_lshrrev_b32_e32 v4, 4, v2
	v_bfe_u32 v5, v2, 4, 2
	v_or_b32_e32 v9, v9, v6
	v_or_b32_e32 v6, v7, v6
	v_mov_b64_e32 v[0:1], v[252:253]
	v_lshlrev_b32_e32 v167, 4, v9
	v_lshlrev_b32_e32 v175, 4, v6
	s_waitcnt vmcnt(17)
	v_lshl_add_u64 v[152:153], s[0:1], 0, v[0:1]
	v_lshl_add_u64 v[154:155], s[14:15], 0, v[0:1]
	v_ashrrev_i32_e32 v0, 3, v2
	v_and_b32_e32 v6, 12, v2
	v_bitop3_b32 v7, v4, v3, 3 bitop3:0x6c
	v_bitop3_b32 v8, v5, v3, 4 bitop3:0x36
	v_bitop3_b32 v9, v5, v3, 8 bitop3:0x36
	v_bitop3_b32 v10, v5, v3, 12 bitop3:0x36
	v_and_b32_e32 v0, -8, v0
	v_add_lshl_u32 v6, v6, v3, 8
	v_lshlrev_b32_e32 v7, 4, v7
	v_lshlrev_b32_e32 v8, 4, v8
	v_lshlrev_b32_e32 v9, 4, v9
	v_lshlrev_b32_e32 v10, 4, v10
	v_add_u32_e32 v0, s77, v0
	v_or_b32_e32 v176, v7, v6
	v_or_b32_e32 v178, v8, v6
	v_or_b32_e32 v180, v9, v6
	v_or_b32_e32 v182, v10, v6
	v_or_b32_e32 v6, 0x2000, v6
	v_add_u32_e32 v1, -15, v0
	v_or3_b32 v184, v7, v6, s8
	v_or3_b32 v185, v8, v6, s8
	v_or3_b32 v186, v9, v6, s8
	v_or3_b32 v187, v10, v6, s8
	v_bfe_u32 v6, v2, 2, 2
	v_ashrrev_i32_e32 v188, 4, v1
	v_add_u32_e32 v1, v1, v6
	v_ashrrev_i32_e32 v189, 4, v1
	v_bfe_u32 v1, v2, 1, 3
	v_bitop3_b32 v2, v4, v1, 3 bitop3:0x6c
	v_bitop3_b32 v1, v5, v1, 4 bitop3:0x36
	v_add_u32_e32 v0, -11, v0
	v_mov_b32_e32 v18, v17
	v_mov_b32_e32 v19, v17
	v_lshlrev_b32_e32 v3, 7, v3
	v_lshlrev_b32_e32 v2, 4, v2
	v_lshlrev_b32_e32 v1, 4, v1
	v_ashrrev_i32_e32 v191, 4, v0
	v_add_u32_e32 v0, v0, v6
	v_mov_b32_e32 v16, v17
	v_mov_b64_e32 v[82:83], v[18:19]
	v_mov_b64_e32 v[78:79], v[18:19]
	v_mov_b64_e32 v[74:75], v[18:19]
	v_mov_b64_e32 v[70:71], v[18:19]
	v_mov_b64_e32 v[66:67], v[18:19]
	v_mov_b64_e32 v[62:63], v[18:19]
	v_mov_b64_e32 v[58:59], v[18:19]
	v_mov_b64_e32 v[54:55], v[18:19]
	v_mov_b64_e32 v[114:115], v[18:19]
	v_mov_b64_e32 v[110:111], v[18:19]
	v_mov_b64_e32 v[106:107], v[18:19]
	v_mov_b64_e32 v[102:103], v[18:19]
	v_mov_b64_e32 v[98:99], v[18:19]
	v_mov_b64_e32 v[94:95], v[18:19]
	v_mov_b64_e32 v[90:91], v[18:19]
	v_mov_b64_e32 v[86:87], v[18:19]
	v_lshlrev_b32_e32 v163, 4, v11
	v_or_b32_e32 v177, 0x400, v176
	v_or_b32_e32 v179, 0x400, v178
	v_or_b32_e32 v181, 0x400, v180
	v_or_b32_e32 v183, 0x400, v182
	v_lshlrev_b32_e32 v190, 3, v5
	v_ashrrev_i32_e32 v192, 4, v0
	s_mov_b32 s79, 0
	v_mov_b32_e32 v195, 0
	v_mov_b32_e32 v196, 0xf149f2ca
	s_mov_b32 s78, 63
	v_add_u32_e32 v193, v3, v2
	v_add_u32_e32 v194, v3, v1
	v_mov_b64_e32 v[80:81], v[16:17]
	v_mov_b64_e32 v[76:77], v[16:17]
	v_mov_b64_e32 v[72:73], v[16:17]
	v_mov_b64_e32 v[68:69], v[16:17]
	v_mov_b64_e32 v[64:65], v[16:17]
	v_mov_b64_e32 v[60:61], v[16:17]
	v_mov_b64_e32 v[56:57], v[16:17]
	v_mov_b64_e32 v[52:53], v[16:17]
	v_mov_b64_e32 v[112:113], v[16:17]
	v_mov_b64_e32 v[108:109], v[16:17]
	v_mov_b64_e32 v[104:105], v[16:17]
	v_mov_b64_e32 v[100:101], v[16:17]
	v_mov_b64_e32 v[96:97], v[16:17]
	v_mov_b64_e32 v[92:93], v[16:17]
	v_mov_b64_e32 v[88:89], v[16:17]
	v_mov_b64_e32 v[84:85], v[16:17]
	v_mov_b32_e32 v16, 0xf149f2ca
	v_mov_b32_e32 v19, 0
.LBB0_1478:
	s_waitcnt vmcnt(4)
	ds_write_b128 v249, v[128:131]
	s_waitcnt vmcnt(3)
	ds_write_b128 v250, v[124:127] offset:4096
	ds_write_b128 v249, v[120:123] offset:8192
	ds_write_b128 v250, v[116:119] offset:12288
	s_waitcnt vmcnt(0)
	ds_write_b128 v251, v[144:147] offset:16384
	ds_write_b128 v251, v[140:143] offset:20480
	ds_write_b128 v251, v[136:139] offset:24576
	ds_write_b128 v251, v[132:135] offset:28672
	s_waitcnt lgkmcnt(0)
	s_barrier
	ds_read_b128 v[0:3], v176
	ds_read_b128 v[4:7], v177
	ds_read_b128 v[8:11], v178
	ds_read_b128 v[12:15], v179
	ds_read_b128 v[124:127], v180
	ds_read_b128 v[132:135], v181
	ds_read_b128 v[144:147], v182
	ds_read_b128 v[148:151], v183
	s_waitcnt lgkmcnt(7)
	v_mfma_f32_16x16x32_bf16 v[0:3], v[0:3], v[20:23], 0
	s_add_i32 s80, s79, 1
	s_cmp_lt_i32 s79, s51
	s_cselect_b32 s56, s80, s79
	s_waitcnt lgkmcnt(6)
	v_mfma_f32_16x16x32_bf16 v[4:7], v[4:7], v[20:23], 0
	s_lshl_b64 s[14:15], s[56:57], 14
	s_waitcnt lgkmcnt(5)
	v_mfma_f32_16x16x32_bf16 v[0:3], v[8:11], v[24:27], v[0:3]
	v_lshl_add_u64 v[8:9], v[152:153], 0, s[14:15]
	v_lshl_add_u64 v[246:247], v[8:9], 0, s[98:99]
	global_load_dwordx4 v[116:119], v[246:247], off
	global_load_dwordx4 v[120:123], v[246:247], off offset:-4096
	s_waitcnt lgkmcnt(4)
	v_mfma_f32_16x16x32_bf16 v[4:7], v[12:15], v[24:27], v[4:7]
	v_lshl_add_u64 v[14:15], v[154:155], 0, s[14:15]
	global_load_dwordx4 v[128:131], v[8:9], off offset:-4096
	v_lshl_add_u64 v[244:245], v[14:15], 0, s[98:99]
	global_load_dwordx4 v[136:139], v[244:245], off offset:-4096
	s_waitcnt lgkmcnt(3)
	v_mfma_f32_16x16x32_bf16 v[0:3], v[124:127], v[28:31], v[0:3]
	global_load_dwordx4 v[124:127], v[8:9], off
	global_load_dwordx4 v[140:143], v[14:15], off
	s_waitcnt lgkmcnt(2)
	v_mfma_f32_16x16x32_bf16 v[10:13], v[132:135], v[28:31], v[4:7]
	global_load_dwordx4 v[132:135], v[244:245], off
	s_waitcnt lgkmcnt(1)
	v_mfma_f32_16x16x32_bf16 v[6:9], v[144:147], v[32:35], v[0:3]
	global_load_dwordx4 v[144:147], v[14:15], off offset:-4096
	s_waitcnt lgkmcnt(0)
	v_mfma_f32_16x16x32_bf16 v[2:5], v[148:151], v[32:35], v[10:13]
	s_nop 2
	ds_read_b128 v[10:13], v176 offset:8192
	ds_read_b128 v[148:151], v184
	ds_read_b128 v[198:201], v178 offset:8192
	ds_read_b128 v[202:205], v185
	ds_read_b128 v[206:209], v180 offset:8192
	ds_read_b128 v[210:213], v186
	ds_read_b128 v[214:217], v182 offset:8192
	ds_read_b128 v[222:225], v187
	s_waitcnt lgkmcnt(7)
	v_mfma_f32_16x16x32_bf16 v[10:13], v[10:13], v[20:23], 0
	s_waitcnt lgkmcnt(6)
	v_mfma_f32_16x16x32_bf16 v[148:151], v[148:151], v[20:23], 0
	s_waitcnt lgkmcnt(5)
	v_mfma_f32_16x16x32_bf16 v[10:13], v[198:201], v[24:27], v[10:13]
	s_waitcnt lgkmcnt(4)
	v_mfma_f32_16x16x32_bf16 v[148:151], v[202:205], v[24:27], v[148:151]
	s_waitcnt lgkmcnt(3)
	v_mfma_f32_16x16x32_bf16 v[10:13], v[206:209], v[28:31], v[10:13]
	s_waitcnt lgkmcnt(2)
	v_mfma_f32_16x16x32_bf16 v[198:201], v[210:213], v[28:31], v[148:151]
	s_waitcnt lgkmcnt(1)
	v_mfma_f32_16x16x32_bf16 v[148:151], v[214:217], v[32:35], v[10:13]
	s_waitcnt lgkmcnt(0)
	v_mfma_f32_16x16x32_bf16 v[10:13], v[222:225], v[32:35], v[198:201]
	v_add_u32_e32 v0, s78, v190
	v_cmp_ge_i32_e32 vcc, s78, v188
	v_subrev_u32_e32 v211, 63, v0
	v_subrev_u32_e32 v210, 62, v0
	v_subrev_u32_e32 v209, 61, v0
	v_subrev_u32_e32 v208, 60, v0
	v_subrev_u32_e32 v207, 59, v0
	v_subrev_u32_e32 v206, 58, v0
	v_subrev_u32_e32 v205, 57, v0
	v_subrev_u32_e32 v204, 56, v0
	v_subrev_u32_e32 v203, 31, v0
	v_subrev_u32_e32 v202, 30, v0
	v_subrev_u32_e32 v201, 29, v0
	v_subrev_u32_e32 v200, 28, v0
	v_subrev_u32_e32 v199, 27, v0
	v_subrev_u32_e32 v198, 26, v0
	v_subrev_u32_e32 v160, 25, v0
	v_subrev_u32_e32 v18, 24, v0
	s_and_saveexec_b64 s[26:27], vcc
	s_xor_b64 s[26:27], exec, s[26:27]
	s_cbranch_execz .LBB0_1480
	v_cmp_gt_i32_e64 s[48:49], v189, v211
	v_cmp_gt_i32_e64 s[46:47], v189, v210
	v_cmp_gt_i32_e64 s[44:45], v189, v209
	v_cmp_gt_i32_e64 s[42:43], v189, v208
	v_cmp_gt_i32_e64 s[40:41], v189, v207
	v_cmp_gt_i32_e64 s[38:39], v189, v206
	v_cmp_gt_i32_e64 s[36:37], v189, v205
	v_cmp_gt_i32_e64 s[34:35], v189, v204
	v_cmp_gt_i32_e64 s[30:31], v189, v203
	v_cmp_gt_i32_e64 s[28:29], v189, v202
	v_cmp_gt_i32_e64 s[24:25], v189, v201
	v_cmp_gt_i32_e64 s[22:23], v189, v200
	v_cmp_gt_i32_e64 s[20:21], v189, v199
	v_cmp_gt_i32_e64 s[18:19], v189, v198
	v_cmp_gt_i32_e64 s[16:17], v189, v160
	v_cmp_gt_i32_e64 s[14:15], v189, v18
	v_cndmask_b32_e64 v6, v169, v6, s[48:49]
	v_cndmask_b32_e64 v7, v169, v7, s[46:47]
	v_cndmask_b32_e64 v8, v169, v8, s[44:45]
	v_cndmask_b32_e64 v9, v169, v9, s[42:43]
	v_cndmask_b32_e64 v2, v169, v2, s[40:41]
	v_cndmask_b32_e64 v3, v169, v3, s[38:39]
	v_cndmask_b32_e64 v4, v169, v4, s[36:37]
	v_cndmask_b32_e64 v5, v169, v5, s[34:35]
	v_cndmask_b32_e64 v148, v169, v148, s[30:31]
	v_cndmask_b32_e64 v149, v169, v149, s[28:29]
	v_cndmask_b32_e64 v150, v169, v150, s[24:25]
	v_cndmask_b32_e64 v151, v169, v151, s[22:23]
	v_cndmask_b32_e64 v10, v169, v10, s[20:21]
	v_cndmask_b32_e64 v11, v169, v11, s[18:19]
	v_cndmask_b32_e64 v12, v169, v12, s[16:17]
	v_cndmask_b32_e64 v13, v169, v13, s[14:15]

.LBB0_1501:
	v_mov_b32_e32 v10, v220
	v_mov_b32_e32 v19, v220
	v_ashrrev_i32_e32 v0, 6, v10
	v_lshl_add_u32 v2, v0, 3, s76
	v_lshrrev_b32_e32 v3, 2, v10
	v_and_or_b32 v2, v3, 3, v2
	v_and_or_b32 v1, v10, 3, s7
	v_mul_lo_u32 v2, v2, 48
	v_mad_u32_u24 v2, v1, 3, v2
	v_ashrrev_i32_e32 v3, 31, v2
	v_lshl_add_u64 v[4:5], v[2:3], 2, s[62:63]
	global_load_dword v11, v[4:5], off
	v_mov_b32_e32 v1, v197
	v_mov_b32_e32 v3, v148
	s_nop 0
	v_permlane32_swap_b32_e32 v197, v1
	v_permlane32_swap_b32_e32 v148, v3
	v_add_f32_e32 v5, v197, v1
	v_add_f32_e32 v4, v148, v3
	v_ashrrev_i32_e32 v1, 31, v0
	v_mov_b32_e32 v7, v5
	v_mov_b32_e32 v6, v4
	v_lshlrev_b64 v[0:1], 6, v[0:1]
	v_permlane16_swap_b32_e32 v5, v7
	v_permlane16_swap_b32_e32 v4, v6
	v_lshl_add_u64 v[8:9], v[0:1], 0, s[58:59]
	v_pk_add_f32 v[0:1], v[4:5], v[6:7]
	v_and_or_b32 v8, v10, 63, v8
	v_div_scale_f32 v6, s[14:15], v1, v1, 1.0
	v_lshlrev_b64 v[4:5], 8, v[8:9]
	v_rcp_f32_e32 v8, v6
	v_add_u32_e32 v2, 0xc0, v2
	v_ashrrev_i32_e32 v3, 31, v2
	v_lshl_add_u64 v[14:15], v[2:3], 2, s[62:63]
	v_fma_f32 v2, -v6, v8, 1.0
	v_div_scale_f32 v7, vcc, 1.0, v1, 1.0
	v_fmac_f32_e32 v8, v2, v8
	v_mul_f32_e32 v2, v7, v8
	v_fma_f32 v3, -v6, v2, v7
	v_fmac_f32_e32 v2, v3, v8
	v_fma_f32 v3, -v6, v2, v7
	v_div_fmas_f32 v2, v3, v8, v2
	v_div_fixup_f32 v2, v2, v1, 1.0
	v_cmp_lt_f32_e32 vcc, 0, v1
	s_waitcnt vmcnt(8)
	v_lshl_add_u64 v[116:117], s[64:65], 0, v[4:5]
	v_cndmask_b32_e32 v18, 0, v2, vcc
	s_waitcnt vmcnt(0)
	v_mul_f32_e32 v16, v11, v18
	v_pk_mul_f32 v[4:5], v[86:87], v[16:17] op_sel_hi:[1,0]
	v_pk_mul_f32 v[2:3], v[84:85], v[16:17] op_sel_hi:[1,0]
	v_pk_mul_f32 v[8:9], v[90:91], v[16:17] op_sel_hi:[1,0]
	v_pk_mul_f32 v[6:7], v[88:89], v[16:17] op_sel_hi:[1,0]
	v_pk_mul_f32 v[12:13], v[94:95], v[16:17] op_sel_hi:[1,0]
	v_pk_mul_f32 v[10:11], v[92:93], v[16:17] op_sel_hi:[1,0]
	v_pk_mul_f32 v[86:87], v[98:99], v[16:17] op_sel_hi:[1,0]
	v_pk_mul_f32 v[84:85], v[96:97], v[16:17] op_sel_hi:[1,0]
	v_pk_mul_f32 v[90:91], v[102:103], v[16:17] op_sel_hi:[1,0]
	v_pk_mul_f32 v[88:89], v[100:101], v[16:17] op_sel_hi:[1,0]
	v_pk_mul_f32 v[94:95], v[106:107], v[16:17] op_sel_hi:[1,0]
	v_pk_mul_f32 v[92:93], v[104:105], v[16:17] op_sel_hi:[1,0]
	v_pk_mul_f32 v[98:99], v[110:111], v[16:17] op_sel_hi:[1,0]
	v_pk_mul_f32 v[96:97], v[108:109], v[16:17] op_sel_hi:[1,0]
	v_pk_mul_f32 v[102:103], v[114:115], v[16:17] op_sel_hi:[1,0]
	v_pk_mul_f32 v[100:101], v[112:113], v[16:17] op_sel_hi:[1,0]
	global_store_dwordx4 v[116:117], v[2:5], off
	global_store_dwordx4 v[116:117], v[6:9], off offset:16
	global_store_dwordx4 v[116:117], v[10:13], off offset:32
	global_store_dwordx4 v[116:117], v[84:87], off offset:48
	global_store_dwordx4 v[116:117], v[88:91], off offset:64
	global_store_dwordx4 v[116:117], v[92:95], off offset:80
	global_store_dwordx4 v[116:117], v[96:99], off offset:96
	global_store_dwordx4 v[116:117], v[100:103], off offset:112
	global_load_dword v1, v[14:15], off
	v_div_scale_f32 v2, s[14:15], v0, v0, 1.0
	v_rcp_f32_e32 v3, v2
	v_div_scale_f32 v4, vcc, 1.0, v0, 1.0
	v_fma_f32 v5, -v2, v3, 1.0
	v_fmac_f32_e32 v3, v5, v3
	v_mul_f32_e32 v5, v4, v3
	v_fma_f32 v6, -v2, v5, v4
	v_fmac_f32_e32 v5, v6, v3
	v_fma_f32 v2, -v2, v5, v4
	v_div_fmas_f32 v2, v2, v3, v5
	v_div_fixup_f32 v2, v2, v0, 1.0
	v_cmp_lt_f32_e32 vcc, 0, v0
	s_nop 1
	v_cndmask_b32_e32 v84, 0, v2, vcc
	s_andn2_b64 vcc, exec, s[12:13]
	s_waitcnt vmcnt(0)
	v_mul_f32_e32 v16, v1, v84
	v_pk_mul_f32 v[2:3], v[54:55], v[16:17] op_sel_hi:[1,0]
	v_pk_mul_f32 v[0:1], v[52:53], v[16:17] op_sel_hi:[1,0]
	v_pk_mul_f32 v[52:53], v[68:69], v[16:17] op_sel_hi:[1,0]
	v_pk_mul_f32 v[6:7], v[58:59], v[16:17] op_sel_hi:[1,0]
	v_pk_mul_f32 v[4:5], v[56:57], v[16:17] op_sel_hi:[1,0]
	v_pk_mul_f32 v[10:11], v[62:63], v[16:17] op_sel_hi:[1,0]
	v_pk_mul_f32 v[8:9], v[60:61], v[16:17] op_sel_hi:[1,0]
	v_pk_mul_f32 v[14:15], v[66:67], v[16:17] op_sel_hi:[1,0]
	v_pk_mul_f32 v[12:13], v[64:65], v[16:17] op_sel_hi:[1,0]
	v_pk_mul_f32 v[54:55], v[70:71], v[16:17] op_sel_hi:[1,0]
	v_pk_mul_f32 v[58:59], v[74:75], v[16:17] op_sel_hi:[1,0]
	v_pk_mul_f32 v[56:57], v[72:73], v[16:17] op_sel_hi:[1,0]
	v_pk_mul_f32 v[62:63], v[78:79], v[16:17] op_sel_hi:[1,0]
	v_pk_mul_f32 v[60:61], v[76:77], v[16:17] op_sel_hi:[1,0]
	v_pk_mul_f32 v[66:67], v[82:83], v[16:17] op_sel_hi:[1,0]
	v_pk_mul_f32 v[64:65], v[80:81], v[16:17] op_sel_hi:[1,0]
	global_store_dwordx4 v[116:117], v[0:3], off offset:128
	global_store_dwordx4 v[116:117], v[4:7], off offset:144
	global_store_dwordx4 v[116:117], v[8:11], off offset:160
	global_store_dwordx4 v[116:117], v[12:15], off offset:176
	global_store_dwordx4 v[116:117], v[52:55], off offset:192
	global_store_dwordx4 v[116:117], v[56:59], off offset:208
	global_store_dwordx4 v[116:117], v[60:63], off offset:224
	global_store_dwordx4 v[116:117], v[64:67], off offset:240
	s_nop 0
	v_lshlrev_b32_e32 v52, 5, v19
	v_ashrrev_i32_e32 v53, 31, v52
	s_cbranch_vccnz .LBB0_1503
	v_lshl_add_u64 v[12:13], v[252:253], 0, s[0:1]
	v_lshl_add_u64 v[246:247], v[12:13], 0, s[98:99]
	global_load_dwordx4 v[0:3], v[246:247], off
	global_load_dwordx4 v[4:7], v[246:247], off offset:-4096
	global_load_dwordx4 v[8:11], v[12:13], off
	s_nop 0
	global_load_dwordx4 v[12:15], v[12:13], off offset:-4096
.LBB0_1503:
	v_and_b32_e32 v90, 63, v19
	v_and_b32_e32 v54, 15, v19
	s_and_b64 vcc, exec, s[10:11]
	v_lshrrev_b32_e32 v72, 2, v54
	v_and_b32_e32 v91, 3, v19
	v_cmp_gt_u32_e64 s[10:11], 16, v90
	s_cbranch_vccz .LBB0_1608
	v_lshrrev_b32_e32 v56, 3, v19
	v_ashrrev_i32_e32 v16, 2, v19
	v_and_b32_e32 v56, 12, v56
	v_lshlrev_b32_e32 v57, 2, v19
	v_and_or_b32 v56, v16, 3, v56
	v_lshlrev_b32_e32 v16, 4, v16
	v_and_b32_e32 v57, 12, v57
	v_bitop3_b32 v58, v56, v16, v57 bitop3:0xde
	v_lshlrev_b32_e32 v92, 4, v58
	v_or_b32_e32 v58, 1, v57
	v_bitop3_b32 v58, v58, v16, v56 bitop3:0xde
	v_lshlrev_b32_e32 v93, 4, v58
	v_or_b32_e32 v58, 2, v57
	v_or_b32_e32 v57, 3, v57
	v_bitop3_b32 v58, v58, v16, v56 bitop3:0xde
	v_bitop3_b32 v16, v57, v16, v56 bitop3:0xde
	v_lshrrev_b32_e32 v55, 4, v90
	v_lshlrev_b32_e32 v95, 4, v16
	v_ashrrev_i32_e32 v16, 3, v19
	v_lshlrev_b32_e32 v94, 4, v58
	v_lshl_add_u64 v[68:69], v[252:253], 0, s[0:1]
	v_and_b32_e32 v16, -8, v16
	v_and_b32_e32 v53, 12, v19
	v_xor_b32_e32 v56, v55, v54
	v_bitop3_b32 v57, v55, v54, 4 bitop3:0x36
	v_bitop3_b32 v58, v55, v54, 8 bitop3:0x36
	v_bitop3_b32 v59, v55, v54, 12 bitop3:0x36
	v_add_u32_e32 v52, s77, v16
	v_add_lshl_u32 v53, v53, v54, 8
	v_lshlrev_b32_e32 v56, 4, v56
	v_lshlrev_b32_e32 v57, 4, v57
	v_lshlrev_b32_e32 v58, 4, v58
	v_lshlrev_b32_e32 v59, 4, v59
	v_add_u32_e32 v16, -15, v52
	v_or_b32_e32 v96, v56, v53
	v_or_b32_e32 v99, v57, v53
	v_or_b32_e32 v101, v58, v53
	v_or_b32_e32 v103, v59, v53
	v_or_b32_e32 v53, 0x2000, v53
	v_or3_b32 v105, v56, v53, s8
	v_or3_b32 v106, v57, v53, s8
	v_or3_b32 v107, v58, v53, s8
	v_or3_b32 v108, v59, v53, s8
	v_ashrrev_i32_e32 v53, 4, v16
	v_max_i32_e32 v109, 0, v53
	v_lshlrev_b32_e32 v110, 3, v55
	v_add_u32_e32 v53, -16, v170
	v_and_b32_e32 v55, 64, v170
	v_and_b32_e32 v98, 3, v19
	v_add_u32_e32 v19, -11, v52
	v_add_u32_e32 v16, v16, v72
	v_cmp_lt_i32_e32 vcc, v53, v55
	v_ashrrev_i32_e32 v52, 4, v19
	v_add_u32_e32 v19, v19, v72
	v_ashrrev_i32_e32 v16, 4, v16
	v_cndmask_b32_e32 v53, v53, v170, vcc
	v_ashrrev_i32_e32 v19, 4, v19
	s_movk_i32 s0, 0x410
	v_max_i32_e32 v16, 0, v16
	v_lshlrev_b32_e32 v112, 2, v53
	v_or_b32_e32 v53, v55, v54
	v_max_i32_e32 v115, 0, v52
	v_max_i32_e32 v70, 0, v19
	v_mad_u32_u24 v52, v72, s0, v158
	v_or_b32_e32 v97, 0x400, v96
	v_or_b32_e32 v100, 0x400, v99
	v_or_b32_e32 v102, 0x400, v101
	v_or_b32_e32 v104, 0x400, v103
	s_mov_b32 s26, 0
	v_lshl_or_b32 v113, v53, 2, v171
	v_cmp_eq_u32_e32 vcc, 0, v98
	v_mov_b32_e32 v71, v70
	v_mov_b32_e32 v85, v84
	v_mov_b32_e32 v73, v16
	v_mov_b32_e32 v19, v18
	v_add3_u32 v116, v52, v110, s5
	v_mov_b32_e32 v111, 0
	s_mov_b32 s27, 0
	v_mov_b32_e32 v114, 0
	s_branch .LBB0_1506

.LBB0_1506:
	s_waitcnt vmcnt(0)
	ds_write_b128 v249, v[12:15]
	ds_write_b128 v250, v[8:11] offset:4096
	ds_write_b128 v249, v[4:7] offset:8192
	ds_write_b128 v250, v[0:3] offset:12288
	s_waitcnt lgkmcnt(0)
	s_barrier
	ds_read_b128 v[0:3], v96
	ds_read_b128 v[4:7], v97
	ds_read_b128 v[8:11], v99
	ds_read_b128 v[12:15], v100
	ds_read_b128 v[52:55], v101
	ds_read_b128 v[56:59], v102
	ds_read_b128 v[60:63], v103
	ds_read_b128 v[74:77], v104
	s_waitcnt lgkmcnt(7)
	v_mfma_f32_16x16x32_bf16 v[0:3], v[0:3], v[20:23], 0
	s_add_i32 s33, s27, 1
	s_cmp_lt_i32 s27, s51
	s_cselect_b32 s56, s33, s27
	s_waitcnt lgkmcnt(6)
	v_mfma_f32_16x16x32_bf16 v[4:7], v[4:7], v[20:23], 0
	s_lshl_b64 s[0:1], s[56:57], 14
	v_lshl_add_u64 v[78:79], v[68:69], 0, s[0:1]
	s_waitcnt lgkmcnt(5)
	v_mfma_f32_16x16x32_bf16 v[0:3], v[8:11], v[24:27], v[0:3]
	v_lshl_add_u64 v[246:247], v[78:79], 0, s[98:99]
	global_load_dwordx4 v[8:11], v[78:79], off
	s_waitcnt lgkmcnt(4)
	v_mfma_f32_16x16x32_bf16 v[4:7], v[12:15], v[24:27], v[4:7]
	s_waitcnt lgkmcnt(3)
	v_mfma_f32_16x16x32_bf16 v[12:15], v[52:55], v[28:31], v[0:3]
	s_waitcnt lgkmcnt(2)
	v_mfma_f32_16x16x32_bf16 v[52:55], v[56:59], v[28:31], v[4:7]
	s_nop 0
	global_load_dwordx4 v[0:3], v[246:247], off
	s_nop 1
	global_load_dwordx4 v[4:7], v[246:247], off offset:-4096
	s_waitcnt lgkmcnt(1)
	v_mfma_f32_16x16x32_bf16 v[64:67], v[60:63], v[32:35], v[12:15]
	s_nop 2
	global_load_dwordx4 v[12:15], v[78:79], off offset:-4096
	s_waitcnt lgkmcnt(0)
	v_mfma_f32_16x16x32_bf16 v[60:63], v[74:77], v[32:35], v[52:55]
	s_nop 2
	ds_read_b128 v[52:55], v96 offset:8192
	ds_read_b128 v[56:59], v105
	ds_read_b128 v[74:77], v99 offset:8192
	ds_read_b128 v[78:81], v106
	ds_read_b128 v[86:89], v101 offset:8192
	ds_read_b128 v[118:121], v107
	ds_read_b128 v[122:125], v103 offset:8192
	ds_read_b128 v[126:129], v108
	s_waitcnt lgkmcnt(7)
	v_mfma_f32_16x16x32_bf16 v[52:55], v[52:55], v[20:23], 0
	s_waitcnt lgkmcnt(6)
	v_mfma_f32_16x16x32_bf16 v[56:59], v[56:59], v[20:23], 0
	s_waitcnt lgkmcnt(5)
	v_mfma_f32_16x16x32_bf16 v[52:55], v[74:77], v[24:27], v[52:55]
	s_waitcnt lgkmcnt(4)
	v_mfma_f32_16x16x32_bf16 v[56:59], v[78:81], v[24:27], v[56:59]
	s_waitcnt lgkmcnt(3)
	v_mfma_f32_16x16x32_bf16 v[52:55], v[86:89], v[28:31], v[52:55]
	s_waitcnt lgkmcnt(2)
	v_mfma_f32_16x16x32_bf16 v[74:77], v[118:121], v[28:31], v[56:59]
	s_waitcnt lgkmcnt(1)
	v_mfma_f32_16x16x32_bf16 v[56:59], v[122:125], v[32:35], v[52:55]
	s_waitcnt lgkmcnt(0)
	v_mfma_f32_16x16x32_bf16 v[52:55], v[126:129], v[32:35], v[74:77]
	s_add_i32 s56, s26, 63
	v_add_u32_e32 v129, s26, v110
	v_cmp_ge_u32_e64 s[0:1], s56, v109
	v_add_u32_e32 v133, 3, v129
	v_add_u32_e32 v128, 4, v129
	v_or_b32_e32 v125, 5, v129
	v_or_b32_e32 v131, 1, v129
	v_or_b32_e32 v126, 6, v129
	v_or_b32_e32 v130, 2, v129
	v_add_u32_e32 v127, 7, v129
	v_or_b32_e32 v117, 36, v129
	v_or_b32_e32 v124, 32, v129
	v_or_b32_e32 v118, 37, v129
	v_or_b32_e32 v123, 33, v129
	v_or_b32_e32 v119, 38, v129
	v_or_b32_e32 v122, 34, v129
	v_or_b32_e32 v120, 39, v129
	v_or_b32_e32 v121, 35, v129
	s_and_saveexec_b64 s[54:55], s[0:1]
	s_xor_b64 s[0:1], exec, s[54:55]
	s_cbranch_execz .LBB0_1508
	v_cmp_lt_u32_e64 s[46:47], v133, v16
	v_cmp_lt_u32_e64 s[44:45], v129, v16
	v_cmp_lt_u32_e64 s[40:41], v131, v16
	v_cmp_lt_u32_e64 s[36:37], v130, v16
	v_cmp_lt_u32_e64 s[48:49], v128, v73
	v_cmp_lt_u32_e64 s[42:43], v125, v73
	v_cmp_lt_u32_e64 s[38:39], v126, v73
	v_cmp_lt_u32_e64 s[34:35], v127, v16
	v_cmp_lt_u32_e64 s[24:25], v124, v16
	v_cmp_lt_u32_e64 s[22:23], v123, v16
	v_cmp_lt_u32_e64 s[18:19], v122, v16
	v_cmp_lt_u32_e64 s[14:15], v121, v16
	v_cmp_lt_u32_e64 s[30:31], v117, v73
	v_cmp_lt_u32_e64 s[28:29], v118, v73
	v_cmp_lt_u32_e64 s[20:21], v119, v73
	v_cmp_lt_u32_e64 s[16:17], v120, v73
	v_cndmask_b32_e64 v67, v169, v67, s[46:47]
	v_cndmask_b32_e64 v64, v169, v64, s[44:45]
	v_cndmask_b32_e64 v65, v169, v65, s[40:41]
	v_cndmask_b32_e64 v66, v169, v66, s[36:37]
	v_cndmask_b32_e64 v60, v169, v60, s[48:49]
	v_cndmask_b32_e64 v61, v169, v61, s[42:43]
	v_cndmask_b32_e64 v62, v169, v62, s[38:39]
	v_cndmask_b32_e64 v63, v169, v63, s[34:35]
	v_cndmask_b32_e64 v56, v169, v56, s[24:25]
	v_cndmask_b32_e64 v57, v169, v57, s[22:23]
	v_cndmask_b32_e64 v58, v169, v58, s[18:19]
	v_cndmask_b32_e64 v59, v169, v59, s[14:15]
	v_cndmask_b32_e64 v52, v169, v52, s[30:31]
	v_cndmask_b32_e64 v53, v169, v53, s[28:29]
	v_cndmask_b32_e64 v54, v169, v54, s[20:21]
	v_cndmask_b32_e64 v55, v169, v55, s[16:17]

.LBB0_1618:
	s_lshl_b64 s[0:1], s[66:67], 22
	s_add_u32 s18, s90, s0
	s_addc_u32 s19, s91, s1
	s_add_u32 s20, s92, s0
	v_cndmask_b32_e64 v0, 0, 1, s[22:23]
	s_addc_u32 s21, s93, s1
	v_cmp_ne_u32_e64 s[0:1], 1, v0
	v_lshlrev_b32_e32 v0, 5, v3
	s_andn2_b64 vcc, exec, s[22:23]
	v_ashrrev_i32_e32 v1, 31, v0
	s_cbranch_vccnz .LBB0_1620
	s_lshl_b32 s24, s94, 14
	s_add_u32 s22, s18, s24
	s_addc_u32 s23, s19, 0
	v_mov_b64_e32 v[6:7], v[252:253]
	v_lshl_add_u64 v[8:9], s[22:23], 0, v[6:7]
	s_add_u32 s22, s20, s24
	s_addc_u32 s23, s21, 0
	v_lshl_add_u64 v[6:7], s[22:23], 0, v[6:7]
	v_lshl_add_u64 v[246:247], v[8:9], 0, s[98:99]
	global_load_dwordx4 v[116:119], v[246:247], off
	global_load_dwordx4 v[120:123], v[246:247], off offset:-4096
	global_load_dwordx4 v[124:127], v[8:9], off
	global_load_dwordx4 v[128:131], v[8:9], off offset:-4096
	v_lshl_add_u64 v[244:245], v[6:7], 0, s[98:99]
	global_load_dwordx4 v[132:135], v[244:245], off
	global_load_dwordx4 v[136:139], v[244:245], off offset:-4096
	global_load_dwordx4 v[140:143], v[6:7], off
	global_load_dwordx4 v[144:147], v[6:7], off offset:-4096
.LBB0_1620:
	s_and_b64 vcc, exec, s[0:1]
	s_cbranch_vccnz .LBB0_1655
	v_lshrrev_b32_e32 v7, 3, v3
	v_ashrrev_i32_e32 v6, 2, v3
	v_and_b32_e32 v7, 12, v7
	v_lshlrev_b32_e32 v9, 2, v3
	v_and_or_b32 v7, v6, 3, v7
	v_lshlrev_b32_e32 v6, 4, v6
	v_and_b32_e32 v10, 12, v9
	v_bitop3_b32 v11, v7, v6, v10 bitop3:0xde
	v_lshlrev_b32_e32 v177, 4, v11
	v_or_b32_e32 v11, 1, v10
	v_bitop3_b32 v11, v11, v6, v7 bitop3:0xde
	v_lshlrev_b32_e32 v178, 4, v11
	v_or_b32_e32 v11, 2, v10
	v_or_b32_e32 v10, 3, v10
	v_bfe_u32 v8, v3, 2, 3
	v_bitop3_b32 v11, v11, v6, v7 bitop3:0xde
	v_bitop3_b32 v6, v10, v6, v7 bitop3:0xde
	v_lshlrev_b32_e32 v180, 4, v6
	v_and_b32_e32 v6, -8, v9
	v_and_b32_e32 v7, 4, v9
	v_bitop3_b32 v9, v9, v8, 4 bitop3:0x6c
	v_or_b32_e32 v9, v9, v6
	v_lshlrev_b32_e32 v181, 4, v9
	v_bitop3_b32 v9, v7, v8, 1 bitop3:0x36
	v_or_b32_e32 v9, v9, v6
	v_lshlrev_b32_e32 v182, 4, v9
	v_bitop3_b32 v9, v7, v8, 2 bitop3:0x36
	v_bitop3_b32 v7, v7, v8, 3 bitop3:0x36
	v_mov_b64_e32 v[0:1], v[252:253]
	v_and_b32_e32 v5, 15, v3
	v_lshrrev_b32_e32 v4, 4, v4
	v_or_b32_e32 v9, v9, v6
	v_or_b32_e32 v6, v7, v6
	v_lshl_add_u64 v[164:165], s[18:19], 0, v[0:1]
	v_lshl_add_u64 v[166:167], s[20:21], 0, v[0:1]
	v_ashrrev_i32_e32 v0, 3, v3
	v_lshlrev_b32_e32 v183, 4, v9
	v_lshlrev_b32_e32 v184, 4, v6
	v_and_b32_e32 v185, -8, v0
	v_and_b32_e32 v1, 12, v3
	v_bitop3_b32 v6, v4, v3, 15 bitop3:0x78
	v_bitop3_b32 v7, v4, v5, 4 bitop3:0x36
	v_bitop3_b32 v8, v4, v5, 8 bitop3:0x36
	v_bitop3_b32 v9, v4, v5, 12 bitop3:0x36
	v_bfe_u32 v0, v3, 2, 2
	v_add_lshl_u32 v1, v1, v5, 8
	v_lshlrev_b32_e32 v6, 4, v6
	v_lshlrev_b32_e32 v7, 4, v7
	v_lshlrev_b32_e32 v8, 4, v8
	v_lshlrev_b32_e32 v9, 4, v9
	v_add_u32_e32 v199, s77, v185
	v_lshlrev_b32_e64 v186, v0, 1
	v_or_b32_e32 v187, v6, v1
	v_or_b32_e32 v189, v7, v1
	v_or_b32_e32 v191, v8, v1
	v_or_b32_e32 v193, v9, v1
	v_or_b32_e32 v1, 0x2000, v1
	v_or_b32_e32 v200, v199, v0
	v_bfe_u32 v0, v3, 1, 3
	v_mov_b32_e32 v18, v17
	v_mov_b32_e32 v19, v17
	v_or3_b32 v195, v6, v1, s8
	v_or3_b32 v196, v7, v1, s8
	v_or3_b32 v197, v8, v1, s8
	v_or3_b32 v198, v9, v1, s8
	v_xor_b32_e32 v1, v4, v0
	v_bitop3_b32 v0, v4, v0, 4 bitop3:0x36
	v_mov_b32_e32 v16, v17
	v_mov_b64_e32 v[54:55], v[18:19]
	v_mov_b64_e32 v[58:59], v[18:19]
	v_mov_b64_e32 v[62:63], v[18:19]
	v_mov_b64_e32 v[66:67], v[18:19]
	v_mov_b64_e32 v[70:71], v[18:19]
	v_mov_b64_e32 v[74:75], v[18:19]
	v_mov_b64_e32 v[78:79], v[18:19]
	v_mov_b64_e32 v[82:83], v[18:19]
	v_mov_b64_e32 v[86:87], v[18:19]
	v_mov_b64_e32 v[90:91], v[18:19]
	v_mov_b64_e32 v[94:95], v[18:19]
	v_mov_b64_e32 v[98:99], v[18:19]
	v_mov_b64_e32 v[102:103], v[18:19]
	v_mov_b64_e32 v[106:107], v[18:19]
	v_mov_b64_e32 v[110:111], v[18:19]
	v_mov_b64_e32 v[114:115], v[18:19]
	v_lshlrev_b32_e32 v179, 4, v11
	v_or_b32_e32 v188, 0x400, v187
	v_or_b32_e32 v190, 0x400, v189
	v_or_b32_e32 v192, 0x400, v191
	v_or_b32_e32 v194, 0x400, v193
	v_lshlrev_b32_e32 v201, 3, v4
	v_lshlrev_b32_e32 v202, 7, v5
	v_lshlrev_b32_e32 v203, 4, v1
	v_lshlrev_b32_e32 v204, 4, v0
	v_or_b32_e32 v205, 4, v200
	v_mov_b32_e32 v175, 0
	v_mov_b32_e32 v206, 0xf149f2ca
	v_mov_b64_e32 v[52:53], v[16:17]
	v_mov_b64_e32 v[56:57], v[16:17]
	v_mov_b64_e32 v[60:61], v[16:17]
	v_mov_b64_e32 v[64:65], v[16:17]
	v_mov_b64_e32 v[68:69], v[16:17]
	v_mov_b64_e32 v[72:73], v[16:17]
	v_mov_b64_e32 v[76:77], v[16:17]
	v_mov_b64_e32 v[80:81], v[16:17]
	v_mov_b64_e32 v[84:85], v[16:17]
	v_mov_b64_e32 v[88:89], v[16:17]
	v_mov_b64_e32 v[92:93], v[16:17]
	v_mov_b64_e32 v[96:97], v[16:17]
	v_mov_b64_e32 v[100:101], v[16:17]
	v_mov_b64_e32 v[104:105], v[16:17]
	v_mov_b64_e32 v[108:109], v[16:17]
	v_mov_b64_e32 v[112:113], v[16:17]
	v_mov_b32_e32 v18, 0xf149f2ca
	v_mov_b32_e32 v176, 0
.LBB0_1622:
	s_cmpk_gt_u32 s94, 0xfe
	s_movk_i32 s95, 0x100
	s_waitcnt vmcnt(4)
	ds_write_b128 v249, v[128:131]
	ds_write_b128 v250, v[124:127] offset:4096
	ds_write_b128 v249, v[120:123] offset:8192
	ds_write_b128 v250, v[116:119] offset:12288
	s_waitcnt vmcnt(0)
	ds_write_b128 v251, v[144:147] offset:16384
	ds_write_b128 v251, v[140:143] offset:20480
	ds_write_b128 v251, v[136:139] offset:24576
	ds_write_b128 v251, v[132:135] offset:28672
	s_waitcnt lgkmcnt(0)
	s_barrier
	s_cbranch_scc1 .LBB0_1632
	s_add_i32 s22, s94, 1
	s_cmp_gt_u32 s94, 62
	s_cselect_b64 s[18:19], -1, 0
	s_lshl_b64 s[0:1], -1, s22
	s_and_b64 s[20:21], s[0:1], s[10:11]
	s_cmp_eq_u64 s[20:21], 0
	s_cselect_b64 s[24:25], -1, 0
	s_or_b64 s[24:25], s[18:19], s[24:25]
	s_mov_b64 s[18:19], -1
	s_and_b64 vcc, exec, s[24:25]
	s_cbranch_vccnz .LBB0_1625
	s_ff1_i32_b64 s95, s[20:21]
	s_mov_b64 s[18:19], 0

.LBB0_1632:
	s_min_u32 s0, s95, 0xff
	s_lshl_b32 s0, s0, 2
	s_add_i32 s18, s0, 0x10200
	s_cmp_gt_u32 s95, s86
	s_cselect_b64 s[78:79], -1, 0
	s_and_b64 s[0:1], s[78:79], exec
	s_cselect_b32 s0, s94, s95
	s_lshl_b32 s56, s0, 14
	v_lshl_add_u64 v[0:1], v[164:165], 0, s[56:57]
	v_lshl_add_u64 v[246:247], v[0:1], 0, s[98:99]
	global_load_dwordx4 v[116:119], v[246:247], off
	global_load_dwordx4 v[120:123], v[246:247], off offset:-4096
	global_load_dwordx4 v[124:127], v[0:1], off
	global_load_dwordx4 v[128:131], v[0:1], off offset:-4096
	v_lshl_add_u64 v[0:1], v[166:167], 0, s[56:57]
	v_lshl_add_u64 v[244:245], v[0:1], 0, s[98:99]
	global_load_dwordx4 v[132:135], v[244:245], off
	global_load_dwordx4 v[136:139], v[244:245], off offset:-4096
	global_load_dwordx4 v[140:143], v[0:1], off
	global_load_dwordx4 v[144:147], v[0:1], off offset:-4096
	v_mov_b32_e32 v0, s18
	ds_read_b32 v19, v0
	v_readfirstlane_b32 s0, v2
	s_nop 1
	v_ashrrev_i32_e64 v207, v185, s0
	v_and_b32_e32 v0, 15, v207
	v_cmp_ne_u32_e32 vcc, 0, v0
	s_and_saveexec_b64 s[80:81], vcc
	s_cbranch_execz .LBB0_1642
	ds_read_b128 v[0:3], v187
	ds_read_b128 v[4:7], v188
	ds_read_b128 v[8:11], v189
	ds_read_b128 v[12:15], v190
	ds_read_b128 v[148:151], v191
	ds_read_b128 v[152:155], v192
	ds_read_b128 v[156:159], v193
	ds_read_b128 v[208:211], v194
	s_waitcnt lgkmcnt(7)
	v_mfma_f32_16x16x32_bf16 v[0:3], v[0:3], v[20:23], 0
	s_waitcnt lgkmcnt(6)
	v_mfma_f32_16x16x32_bf16 v[4:7], v[4:7], v[20:23], 0
	s_waitcnt lgkmcnt(5)
	v_mfma_f32_16x16x32_bf16 v[0:3], v[8:11], v[24:27], v[0:3]
	s_waitcnt lgkmcnt(4)
	v_mfma_f32_16x16x32_bf16 v[4:7], v[12:15], v[24:27], v[4:7]
	s_waitcnt lgkmcnt(3)
	v_mfma_f32_16x16x32_bf16 v[0:3], v[148:151], v[28:31], v[0:3]
	s_waitcnt lgkmcnt(2)
	v_mfma_f32_16x16x32_bf16 v[4:7], v[152:155], v[28:31], v[4:7]
	s_waitcnt lgkmcnt(1)
	v_mfma_f32_16x16x32_bf16 v[160:163], v[156:159], v[32:35], v[0:3]
	s_waitcnt lgkmcnt(0)
	v_mfma_f32_16x16x32_bf16 v[156:159], v[208:211], v[32:35], v[4:7]
	s_nop 1
	v_and_b32_e32 v0, v207, v186
	v_cmp_ne_u32_e64 s[82:83], 0, v0
	ds_read_b128 v[0:3], v187 offset:8192
	ds_read_b128 v[4:7], v195
	ds_read_b128 v[8:11], v189 offset:8192
	ds_read_b128 v[12:15], v196
	ds_read_b128 v[148:151], v191 offset:8192
	ds_read_b128 v[152:155], v197
	ds_read_b128 v[208:211], v193 offset:8192
	ds_read_b128 v[212:215], v198
	s_waitcnt lgkmcnt(7)
	v_mfma_f32_16x16x32_bf16 v[0:3], v[0:3], v[20:23], 0
	s_waitcnt lgkmcnt(6)
	v_mfma_f32_16x16x32_bf16 v[4:7], v[4:7], v[20:23], 0
	s_waitcnt lgkmcnt(5)
	v_mfma_f32_16x16x32_bf16 v[0:3], v[8:11], v[24:27], v[0:3]
	s_waitcnt lgkmcnt(4)
	v_mfma_f32_16x16x32_bf16 v[4:7], v[12:15], v[24:27], v[4:7]
	s_waitcnt lgkmcnt(3)
	v_mfma_f32_16x16x32_bf16 v[0:3], v[148:151], v[28:31], v[0:3]
	s_waitcnt lgkmcnt(2)
	v_mfma_f32_16x16x32_bf16 v[4:7], v[152:155], v[28:31], v[4:7]
	s_waitcnt lgkmcnt(1)
	v_mfma_f32_16x16x32_bf16 v[152:155], v[208:211], v[32:35], v[0:3]
	s_waitcnt lgkmcnt(0)
	v_mfma_f32_16x16x32_bf16 v[148:151], v[212:215], v[32:35], v[4:7]
	s_lshl_b32 s33, s94, 6
	s_or_b32 s0, s33, 63
	v_cmp_le_i32_e32 vcc, s0, v199
	s_and_saveexec_b64 s[0:1], vcc
	s_xor_b64 s[0:1], exec, s[0:1]
	s_or_saveexec_b64 s[26:27], s[0:1]
	s_mov_b64 s[0:1], s[82:83]
	s_mov_b64 s[18:19], s[82:83]
	s_mov_b64 s[20:21], s[82:83]
	s_mov_b64 s[22:23], s[82:83]
	s_mov_b64 s[24:25], s[82:83]
	s_mov_b64 s[28:29], s[82:83]
	s_mov_b64 s[30:31], s[82:83]
	s_mov_b64 s[34:35], s[82:83]
	s_mov_b64 s[36:37], s[82:83]
	s_mov_b64 s[38:39], s[82:83]
	s_mov_b64 s[40:41], s[82:83]
	s_mov_b64 s[42:43], s[82:83]
	s_mov_b64 s[44:45], s[82:83]
	s_mov_b64 s[46:47], s[82:83]
	s_mov_b64 s[48:49], s[82:83]
	s_mov_b64 s[50:51], s[82:83]
	s_mov_b64 s[84:85], s[82:83]
	s_xor_b64 exec, exec, s[26:27]
	s_cbranch_execz .LBB0_1635
	v_cndmask_b32_e64 v1, 0, -1, s[82:83]
	v_or_b32_e32 v2, s33, v201
	v_cndmask_b32_e64 v0, -1, v200, s[82:83]
	v_cmp_gt_i32_e64 s[0:1], v2, v1
	v_or_b32_e32 v1, 2, v2
	v_cmp_le_i32_e64 s[20:21], v1, v0
	v_or_b32_e32 v1, 3, v2
	v_cmp_le_i32_e64 s[22:23], v1, v0
	v_or_b32_e32 v1, 4, v2
	v_cmp_le_i32_e64 s[24:25], v1, v0
	v_or_b32_e32 v1, 5, v2
	v_cmp_le_i32_e64 s[28:29], v1, v0
	v_or_b32_e32 v1, 6, v2
	v_cmp_le_i32_e64 s[30:31], v1, v0
	v_or_b32_e32 v1, 7, v2
	v_cmp_le_i32_e64 s[34:35], v1, v0
	v_or_b32_e32 v1, 32, v2
	v_cmp_le_i32_e64 s[36:37], v1, v0
	v_cmp_lt_i32_e64 s[38:39], v1, v0
	v_or_b32_e32 v1, 34, v2
	v_cmp_le_i32_e64 s[40:41], v1, v0
	v_or_b32_e32 v1, 35, v2
	v_cmp_le_i32_e64 s[42:43], v1, v0
	v_or_b32_e32 v1, 36, v2
	v_cmp_le_i32_e64 s[44:45], v1, v0
	v_or_b32_e32 v1, 37, v2
	v_cmp_le_i32_e64 s[46:47], v1, v0
	v_or_b32_e32 v1, 38, v2
	v_cmp_le_i32_e64 s[18:19], v2, v0
	v_cmp_le_i32_e64 s[48:49], v1, v0
	v_or_b32_e32 v1, 39, v2
	s_and_b64 s[0:1], s[0:1], s[18:19]
	v_cmp_lt_i32_e64 s[18:19], v2, v0
	v_cmp_le_i32_e64 s[50:51], v1, v0
	v_cndmask_b32_e64 v160, v169, v160, s[0:1]
	v_cndmask_b32_e64 v161, v169, v161, s[18:19]
	v_cndmask_b32_e64 v162, v169, v162, s[20:21]
	v_cndmask_b32_e64 v163, v169, v163, s[22:23]
	v_cndmask_b32_e64 v156, v169, v156, s[24:25]
	v_cndmask_b32_e64 v157, v169, v157, s[28:29]
	v_cndmask_b32_e64 v158, v169, v158, s[30:31]
	v_cndmask_b32_e64 v159, v169, v159, s[34:35]
	v_cndmask_b32_e64 v152, v169, v152, s[36:37]
	v_cndmask_b32_e64 v153, v169, v153, s[38:39]
	v_cndmask_b32_e64 v154, v169, v154, s[40:41]
	v_cndmask_b32_e64 v155, v169, v155, s[42:43]
	v_cndmask_b32_e64 v148, v169, v148, s[44:45]
	v_cndmask_b32_e64 v149, v169, v149, s[46:47]
	v_cndmask_b32_e64 v150, v169, v150, s[48:49]
	v_cndmask_b32_e64 v151, v169, v151, s[50:51]
	s_andn2_b64 s[54:55], s[82:83], exec
	s_and_b64 s[50:51], s[50:51], exec
	s_and_b64 s[48:49], s[48:49], exec
	s_and_b64 s[46:47], s[46:47], exec
	s_and_b64 s[44:45], s[44:45], exec
	s_and_b64 s[42:43], s[42:43], exec
	s_and_b64 s[40:41], s[40:41], exec
	s_and_b64 s[38:39], s[38:39], exec
	s_and_b64 s[36:37], s[36:37], exec
	s_and_b64 s[34:35], s[34:35], exec
	s_and_b64 s[30:31], s[30:31], exec
	s_and_b64 s[28:29], s[28:29], exec
	s_and_b64 s[24:25], s[24:25], exec
	s_and_b64 s[22:23], s[22:23], exec
	s_and_b64 s[20:21], s[20:21], exec
	s_and_b64 s[18:19], s[18:19], exec
	s_and_b64 s[0:1], s[0:1], exec
	s_or_b64 s[84:85], s[82:83], exec
	s_or_b64 s[50:51], s[54:55], s[50:51]
	s_or_b64 s[48:49], s[54:55], s[48:49]
	s_or_b64 s[46:47], s[54:55], s[46:47]
	s_or_b64 s[44:45], s[54:55], s[44:45]
	s_or_b64 s[42:43], s[54:55], s[42:43]
	s_or_b64 s[40:41], s[54:55], s[40:41]
	s_or_b64 s[38:39], s[54:55], s[38:39]
	s_or_b64 s[36:37], s[54:55], s[36:37]
	s_or_b64 s[34:35], s[54:55], s[34:35]
	s_or_b64 s[30:31], s[54:55], s[30:31]
	s_or_b64 s[28:29], s[54:55], s[28:29]
	s_or_b64 s[24:25], s[54:55], s[24:25]
	s_or_b64 s[22:23], s[54:55], s[22:23]
	s_or_b64 s[20:21], s[54:55], s[20:21]
	s_or_b64 s[18:19], s[54:55], s[18:19]
	s_or_b64 s[0:1], s[54:55], s[0:1]

.LBB0_1656:
	v_mov_b32_e32 v4, v220
	s_lshl_b64 s[0:1], s[66:67], 21
	v_ashrrev_i32_e32 v0, 6, v4
	s_waitcnt lgkmcnt(0)
	v_lshl_add_u32 v2, v0, 3, s76
	v_lshrrev_b32_e32 v3, 2, v4
	v_and_or_b32 v2, v3, 3, v2
	v_and_or_b32 v1, v4, 3, s7
	v_mul_lo_u32 v2, v2, 48
	s_waitcnt vmcnt(0)
	v_mad_u32_u24 v14, v1, 3, v2
	v_ashrrev_i32_e32 v15, 31, v14
	v_lshl_add_u64 v[2:3], v[14:15], 2, s[62:63]
	global_load_dword v16, v[2:3], off offset:4
	v_ashrrev_i32_e32 v1, 31, v0
	v_lshlrev_b64 v[0:1], 6, v[0:1]
	v_lshl_add_u64 v[0:1], v[0:1], 0, s[58:59]
	v_and_or_b32 v0, v4, 63, v0
	v_lshlrev_b64 v[0:1], 8, v[0:1]
	v_lshl_add_u64 v[0:1], s[64:65], 0, v[0:1]
	global_load_dwordx4 v[2:5], v[0:1], off
	global_load_dwordx4 v[6:9], v[0:1], off offset:16
	global_load_dwordx4 v[10:13], v[0:1], off offset:32
	global_load_dwordx4 v[116:119], v[0:1], off offset:48
	global_load_dwordx4 v[120:123], v[0:1], off offset:64
	global_load_dwordx4 v[124:127], v[0:1], off offset:80
	global_load_dwordx4 v[128:131], v[0:1], off offset:96
	global_load_dwordx4 v[132:135], v[0:1], off offset:112
	v_mov_b32_e32 v15, v176
	s_nop 1
	v_permlane32_swap_b32_e32 v176, v15
	v_add_f32_e32 v15, v176, v15
	v_mov_b32_e32 v18, v15
	s_nop 1
	v_permlane16_swap_b32_e32 v15, v18
	v_add_f32_e32 v18, v15, v18
	v_add_u32_e32 v14, 0xc0, v14
	v_ashrrev_i32_e32 v15, 31, v14
	v_lshl_add_u64 v[14:15], v[14:15], 2, s[62:63]
	s_waitcnt vmcnt(8)
	v_div_scale_f32 v19, s[10:11], v18, v18, v16
	v_rcp_f32_e32 v136, v19
	v_div_scale_f32 v137, vcc, v16, v18, v16
	s_max_i32 s10, s77, 0x1ff
	v_fma_f32 v138, -v19, v136, 1.0
	v_fmac_f32_e32 v136, v138, v136
	v_mul_f32_e32 v138, v137, v136
	v_fma_f32 v139, -v19, v138, v137
	v_fmac_f32_e32 v138, v139, v136
	v_fma_f32 v19, -v19, v138, v137
	v_div_fmas_f32 v19, v19, v136, v138
	v_div_fixup_f32 v16, v19, v18, v16
	s_waitcnt vmcnt(7)
	v_pk_fma_f32 v[4:5], v[114:115], v[16:17], v[4:5] op_sel_hi:[1,0,1]
	v_pk_fma_f32 v[2:3], v[112:113], v[16:17], v[2:3] op_sel_hi:[1,0,1]
	s_waitcnt vmcnt(6)
	v_pk_fma_f32 v[8:9], v[110:111], v[16:17], v[8:9] op_sel_hi:[1,0,1]
	v_pk_fma_f32 v[6:7], v[108:109], v[16:17], v[6:7] op_sel_hi:[1,0,1]
	s_waitcnt vmcnt(5)
	v_pk_fma_f32 v[12:13], v[106:107], v[16:17], v[12:13] op_sel_hi:[1,0,1]
	v_pk_fma_f32 v[10:11], v[104:105], v[16:17], v[10:11] op_sel_hi:[1,0,1]
	s_waitcnt vmcnt(4)
	v_pk_fma_f32 v[102:103], v[102:103], v[16:17], v[118:119] op_sel_hi:[1,0,1]
	v_pk_fma_f32 v[100:101], v[100:101], v[16:17], v[116:117] op_sel_hi:[1,0,1]
	s_waitcnt vmcnt(3)
	v_pk_fma_f32 v[98:99], v[98:99], v[16:17], v[122:123] op_sel_hi:[1,0,1]
	v_pk_fma_f32 v[96:97], v[96:97], v[16:17], v[120:121] op_sel_hi:[1,0,1]
	s_waitcnt vmcnt(2)
	v_pk_fma_f32 v[94:95], v[94:95], v[16:17], v[126:127] op_sel_hi:[1,0,1]
	v_pk_fma_f32 v[92:93], v[92:93], v[16:17], v[124:125] op_sel_hi:[1,0,1]
	s_waitcnt vmcnt(1)
	v_pk_fma_f32 v[90:91], v[90:91], v[16:17], v[130:131] op_sel_hi:[1,0,1]
	v_pk_fma_f32 v[88:89], v[88:89], v[16:17], v[128:129] op_sel_hi:[1,0,1]
	s_waitcnt vmcnt(0)
	v_pk_fma_f32 v[86:87], v[86:87], v[16:17], v[134:135] op_sel_hi:[1,0,1]
	v_pk_fma_f32 v[84:85], v[84:85], v[16:17], v[132:133] op_sel_hi:[1,0,1]
	global_store_dwordx4 v[0:1], v[2:5], off
	global_store_dwordx4 v[0:1], v[6:9], off offset:16
	global_store_dwordx4 v[0:1], v[10:13], off offset:32
	global_store_dwordx4 v[0:1], v[100:103], off offset:48
	global_store_dwordx4 v[0:1], v[96:99], off offset:64
	global_store_dwordx4 v[0:1], v[92:95], off offset:80
	global_store_dwordx4 v[0:1], v[88:91], off offset:96
	global_store_dwordx4 v[0:1], v[84:87], off offset:112
	global_load_dword v3, v[14:15], off offset:4
	global_load_dwordx4 v[4:7], v[0:1], off offset:128
	global_load_dwordx4 v[8:11], v[0:1], off offset:144
	s_nop 0
	global_load_dwordx4 v[12:15], v[0:1], off offset:160
	global_load_dwordx4 v[84:87], v[0:1], off offset:176
	global_load_dwordx4 v[88:91], v[0:1], off offset:192
	global_load_dwordx4 v[92:95], v[0:1], off offset:208
	global_load_dwordx4 v[96:99], v[0:1], off offset:224
	global_load_dwordx4 v[100:103], v[0:1], off offset:240
	v_mov_b32_e32 v16, v175
	s_nop 1
	v_permlane32_swap_b32_e32 v175, v16
	v_add_f32_e32 v16, v175, v16
	v_mov_b32_e32 v18, v16
	s_nop 1
	v_permlane16_swap_b32_e32 v16, v18
	v_add_f32_e32 v16, v16, v18
	s_addk_i32 s10, 0xfe01
	s_lshr_b32 s10, s10, 6
	v_mov_b32_e32 v2, v220
	s_cmp_gt_i32 s10, s86
	s_waitcnt vmcnt(8)
	v_div_scale_f32 v18, s[12:13], v16, v16, v3
	v_rcp_f32_e32 v19, v18
	v_div_scale_f32 v104, vcc, v3, v16, v3
	v_fma_f32 v105, -v18, v19, 1.0
	v_fmac_f32_e32 v19, v105, v19
	v_mul_f32_e32 v105, v104, v19
	v_fma_f32 v106, -v18, v105, v104
	v_fmac_f32_e32 v105, v106, v19
	v_fma_f32 v18, -v18, v105, v104
	v_div_fmas_f32 v18, v18, v19, v105
	v_div_fixup_f32 v16, v18, v16, v3
	s_waitcnt vmcnt(7)
	v_pk_fma_f32 v[6:7], v[82:83], v[16:17], v[6:7] op_sel_hi:[1,0,1]
	v_pk_fma_f32 v[4:5], v[80:81], v[16:17], v[4:5] op_sel_hi:[1,0,1]
	s_waitcnt vmcnt(6)
	v_pk_fma_f32 v[10:11], v[78:79], v[16:17], v[10:11] op_sel_hi:[1,0,1]
	v_pk_fma_f32 v[8:9], v[76:77], v[16:17], v[8:9] op_sel_hi:[1,0,1]
	s_waitcnt vmcnt(5)
	v_pk_fma_f32 v[14:15], v[74:75], v[16:17], v[14:15] op_sel_hi:[1,0,1]
	v_pk_fma_f32 v[12:13], v[72:73], v[16:17], v[12:13] op_sel_hi:[1,0,1]
	s_waitcnt vmcnt(4)
	v_pk_fma_f32 v[70:71], v[70:71], v[16:17], v[86:87] op_sel_hi:[1,0,1]
	v_pk_fma_f32 v[68:69], v[68:69], v[16:17], v[84:85] op_sel_hi:[1,0,1]
	s_waitcnt vmcnt(3)
	v_pk_fma_f32 v[64:65], v[64:65], v[16:17], v[88:89] op_sel_hi:[1,0,1]
	v_pk_fma_f32 v[66:67], v[66:67], v[16:17], v[90:91] op_sel_hi:[1,0,1]
	s_waitcnt vmcnt(2)
	v_pk_fma_f32 v[60:61], v[60:61], v[16:17], v[92:93] op_sel_hi:[1,0,1]
	v_pk_fma_f32 v[62:63], v[62:63], v[16:17], v[94:95] op_sel_hi:[1,0,1]
	s_waitcnt vmcnt(1)
	v_pk_fma_f32 v[56:57], v[56:57], v[16:17], v[96:97] op_sel_hi:[1,0,1]
	v_pk_fma_f32 v[58:59], v[58:59], v[16:17], v[98:99] op_sel_hi:[1,0,1]
	s_waitcnt vmcnt(0)
	v_pk_fma_f32 v[52:53], v[52:53], v[16:17], v[100:101] op_sel_hi:[1,0,1]
	v_pk_fma_f32 v[54:55], v[54:55], v[16:17], v[102:103] op_sel_hi:[1,0,1]
	global_store_dwordx4 v[0:1], v[4:7], off offset:128
	global_store_dwordx4 v[0:1], v[8:11], off offset:144
	global_store_dwordx4 v[0:1], v[12:15], off offset:160
	global_store_dwordx4 v[0:1], v[68:71], off offset:176
	global_store_dwordx4 v[0:1], v[64:67], off offset:192
	global_store_dwordx4 v[0:1], v[60:63], off offset:208
	global_store_dwordx4 v[0:1], v[56:59], off offset:224
	global_store_dwordx4 v[0:1], v[52:55], off offset:240
	s_cbranch_scc1 .LBB0_1466
	s_lshl_b64 s[12:13], s[0:1], 1
	v_readlane_b32 s0, v254, 22
	s_add_u32 s0, s0, s12
	v_readlane_b32 s1, v254, 26
	s_addc_u32 s1, s1, s13
	s_add_u32 s12, s96, s12
	v_lshrrev_b32_e32 v0, 3, v2
	s_mov_b32 s11, s57
	s_addc_u32 s13, s97, s13
	v_ashrrev_i32_e32 v6, 2, v2
	v_and_b32_e32 v0, 12, v0
	s_lshl_b64 s[14:15], s[10:11], 14
	v_and_or_b32 v7, v6, 3, v0
	s_add_u32 s16, s12, s14
	v_lshlrev_b32_e32 v0, 5, v2
	s_addc_u32 s17, s13, s15
	v_ashrrev_i32_e32 v1, 31, v0
	v_mov_b64_e32 v[0:1], v[252:253]
	s_add_u32 s14, s0, s14
	v_lshl_add_u64 v[4:5], s[16:17], 0, v[0:1]
	s_addc_u32 s15, s1, s15
	v_lshl_add_u64 v[246:247], v[4:5], 0, s[98:99]
	global_load_dwordx4 v[116:119], v[246:247], off
	global_load_dwordx4 v[120:123], v[246:247], off offset:-4096
	global_load_dwordx4 v[124:127], v[4:5], off
	global_load_dwordx4 v[128:131], v[4:5], off offset:-4096
	v_lshl_add_u64 v[4:5], s[14:15], 0, v[0:1]
	v_lshl_add_u64 v[244:245], v[4:5], 0, s[98:99]
	global_load_dwordx4 v[132:135], v[244:245], off
	global_load_dwordx4 v[136:139], v[244:245], off offset:-4096
	global_load_dwordx4 v[140:143], v[4:5], off
	global_load_dwordx4 v[144:147], v[4:5], off offset:-4096
	v_lshlrev_b32_e32 v5, 2, v2
	v_lshlrev_b32_e32 v4, 4, v6
	v_and_b32_e32 v6, 12, v5
	v_bitop3_b32 v11, v7, v4, v6 bitop3:0xde
	v_lshlrev_b32_e32 v156, 4, v11
	v_or_b32_e32 v11, 1, v6
	v_bitop3_b32 v11, v11, v4, v7 bitop3:0xde
	v_lshlrev_b32_e32 v157, 4, v11
	v_or_b32_e32 v11, 2, v6
	v_or_b32_e32 v6, 3, v6
	v_bfe_u32 v3, v2, 2, 3
	v_bitop3_b32 v11, v11, v4, v7 bitop3:0xde
	v_bitop3_b32 v4, v6, v4, v7 bitop3:0xde
	v_lshlrev_b32_e32 v159, 4, v4
	v_and_b32_e32 v4, -8, v5
	v_and_b32_e32 v6, 4, v5
	v_bitop3_b32 v5, v5, v3, 4 bitop3:0x6c
	v_or_b32_e32 v5, v5, v4
	v_lshlrev_b32_e32 v160, 4, v5
	v_bitop3_b32 v5, v6, v3, 1 bitop3:0x36
	v_or_b32_e32 v5, v5, v4
	v_lshlrev_b32_e32 v161, 4, v5
	v_bitop3_b32 v5, v6, v3, 2 bitop3:0x36
	v_bitop3_b32 v3, v6, v3, 3 bitop3:0x36
	v_lshl_add_u64 v[152:153], s[12:13], 0, v[0:1]
	v_lshl_add_u64 v[154:155], s[0:1], 0, v[0:1]
	v_ashrrev_i32_e32 v0, 3, v2
	v_lshrrev_b32_e32 v8, 4, v2
	v_bfe_u32 v9, v2, 4, 2
	v_and_b32_e32 v10, 15, v2
	v_or_b32_e32 v5, v5, v4
	v_or_b32_e32 v3, v3, v4
	v_and_b32_e32 v0, -8, v0
	v_lshlrev_b32_e32 v162, 4, v5
	v_lshlrev_b32_e32 v163, 4, v3
	v_add_u32_e32 v164, s77, v0
	v_and_b32_e32 v0, 12, v2
	v_bitop3_b32 v1, v8, v10, 3 bitop3:0x6c
	v_bitop3_b32 v3, v9, v10, 4 bitop3:0x36
	v_bitop3_b32 v4, v9, v10, 8 bitop3:0x36
	v_bitop3_b32 v5, v9, v10, 12 bitop3:0x36
	v_add_lshl_u32 v0, v0, v10, 8
	v_lshlrev_b32_e32 v1, 4, v1
	v_lshlrev_b32_e32 v3, 4, v3
	v_lshlrev_b32_e32 v4, 4, v4
	v_lshlrev_b32_e32 v5, 4, v5
	v_or_b32_e32 v165, v1, v0
	v_or_b32_e32 v167, v3, v0
	v_or_b32_e32 v176, v4, v0
	v_or_b32_e32 v178, v5, v0
	v_or_b32_e32 v0, 0x2000, v0
	v_or3_b32 v180, v1, v0, s8
	v_or3_b32 v181, v3, v0, s8
	v_or3_b32 v182, v4, v0, s8
	v_or3_b32 v183, v5, v0, s8
	v_bfe_u32 v0, v2, 2, 2
	v_or_b32_e32 v185, v164, v0
	v_bfe_u32 v0, v2, 1, 3
	v_bitop3_b32 v1, v8, v0, 3 bitop3:0x6c
	v_bitop3_b32 v0, v9, v0, 4 bitop3:0x36
	v_mov_b32_e32 v18, v17
	v_mov_b32_e32 v19, v17
	v_lshlrev_b32_e32 v2, 7, v10
	v_lshlrev_b32_e32 v1, 4, v1
	v_lshlrev_b32_e32 v0, 4, v0
	v_mov_b32_e32 v16, v17
	v_mov_b64_e32 v[54:55], v[18:19]
	v_mov_b64_e32 v[58:59], v[18:19]
	v_mov_b64_e32 v[62:63], v[18:19]
	v_mov_b64_e32 v[66:67], v[18:19]
	v_mov_b64_e32 v[70:71], v[18:19]
	v_mov_b64_e32 v[74:75], v[18:19]
	v_mov_b64_e32 v[78:79], v[18:19]
	v_mov_b64_e32 v[82:83], v[18:19]
	v_mov_b64_e32 v[86:87], v[18:19]
	v_mov_b64_e32 v[90:91], v[18:19]
	v_mov_b64_e32 v[94:95], v[18:19]
	v_mov_b64_e32 v[98:99], v[18:19]
	v_mov_b64_e32 v[102:103], v[18:19]
	v_mov_b64_e32 v[106:107], v[18:19]
	v_mov_b64_e32 v[110:111], v[18:19]
	v_mov_b64_e32 v[114:115], v[18:19]
	v_lshlrev_b32_e32 v158, 4, v11
	v_or_b32_e32 v166, 0x400, v165
	v_or_b32_e32 v175, 0x400, v167
	v_or_b32_e32 v177, 0x400, v176
	v_or_b32_e32 v179, 0x400, v178
	v_add_u32_e32 v184, 0xfffffe03, v164
	v_add_u32_e32 v186, 0xfffffe00, v185
	v_lshlrev_b32_e32 v187, 3, v9
	v_add_u32_e32 v188, 0xfffffe07, v164
	v_or_b32_e32 v189, 4, v185
	v_add_u32_e32 v190, 0xfffffe04, v185
	s_lshl_b32 s11, s10, 6
	v_mov_b32_e32 v193, 0
	v_mov_b32_e32 v194, 0xf149f2ca
	v_add_u32_e32 v191, v2, v1
	v_add_u32_e32 v192, v2, v0
	v_mov_b64_e32 v[52:53], v[16:17]
	v_mov_b64_e32 v[56:57], v[16:17]
	v_mov_b64_e32 v[60:61], v[16:17]
	v_mov_b64_e32 v[64:65], v[16:17]
	v_mov_b64_e32 v[68:69], v[16:17]
	v_mov_b64_e32 v[72:73], v[16:17]
	v_mov_b64_e32 v[76:77], v[16:17]
	v_mov_b64_e32 v[80:81], v[16:17]
	v_mov_b64_e32 v[84:85], v[16:17]
	v_mov_b64_e32 v[88:89], v[16:17]
	v_mov_b64_e32 v[92:93], v[16:17]
	v_mov_b64_e32 v[96:97], v[16:17]
	v_mov_b64_e32 v[100:101], v[16:17]
	v_mov_b64_e32 v[104:105], v[16:17]
	v_mov_b64_e32 v[108:109], v[16:17]
	v_mov_b64_e32 v[112:113], v[16:17]
	v_mov_b32_e32 v16, 0xf149f2ca
	v_mov_b32_e32 v19, 0
.LBB0_1658:
	s_waitcnt vmcnt(4)
	ds_write_b128 v249, v[128:131]
	ds_write_b128 v250, v[124:127] offset:4096
	ds_write_b128 v249, v[120:123] offset:8192
	ds_write_b128 v250, v[116:119] offset:12288
	s_waitcnt vmcnt(0)
	ds_write_b128 v251, v[144:147] offset:16384
	ds_write_b128 v251, v[140:143] offset:20480
	ds_write_b128 v251, v[136:139] offset:24576
	ds_write_b128 v251, v[132:135] offset:28672
	s_waitcnt lgkmcnt(0)
	s_barrier
	ds_read_b128 v[0:3], v165
	ds_read_b128 v[4:7], v166
	ds_read_b128 v[8:11], v167
	ds_read_b128 v[12:15], v175
	ds_read_b128 v[124:127], v176
	ds_read_b128 v[132:135], v177
	ds_read_b128 v[144:147], v178
	ds_read_b128 v[148:151], v179
	s_waitcnt lgkmcnt(7)
	v_mfma_f32_16x16x32_bf16 v[0:3], v[0:3], v[20:23], 0
	s_mov_b32 s0, s10
	s_add_i32 s10, s10, 1
	s_cmp_ge_i32 s0, s86
	s_waitcnt lgkmcnt(6)
	v_mfma_f32_16x16x32_bf16 v[4:7], v[4:7], v[20:23], 0
	s_cselect_b64 s[12:13], -1, 0
	s_cmp_lt_i32 s0, s86
	s_cselect_b32 s56, s10, s0
	s_waitcnt lgkmcnt(5)
	v_mfma_f32_16x16x32_bf16 v[0:3], v[8:11], v[24:27], v[0:3]
	s_lshl_b64 s[0:1], s[56:57], 14
	v_lshl_add_u64 v[8:9], v[152:153], 0, s[0:1]
	v_lshl_add_u64 v[246:247], v[8:9], 0, s[98:99]
	global_load_dwordx4 v[116:119], v[246:247], off
	s_waitcnt lgkmcnt(4)
	v_mfma_f32_16x16x32_bf16 v[4:7], v[12:15], v[24:27], v[4:7]
	v_lshl_add_u64 v[14:15], v[154:155], 0, s[0:1]
	global_load_dwordx4 v[120:123], v[246:247], off offset:-4096
	global_load_dwordx4 v[128:131], v[8:9], off offset:-4096
	s_waitcnt lgkmcnt(3)
	v_mfma_f32_16x16x32_bf16 v[0:3], v[124:127], v[28:31], v[0:3]
	global_load_dwordx4 v[124:127], v[8:9], off
	v_lshl_add_u64 v[244:245], v[14:15], 0, s[98:99]
	global_load_dwordx4 v[136:139], v[244:245], off offset:-4096
	global_load_dwordx4 v[140:143], v[14:15], off
	s_waitcnt lgkmcnt(2)
	v_mfma_f32_16x16x32_bf16 v[10:13], v[132:135], v[28:31], v[4:7]
	global_load_dwordx4 v[132:135], v[244:245], off
	s_waitcnt lgkmcnt(1)
	v_mfma_f32_16x16x32_bf16 v[6:9], v[144:147], v[32:35], v[0:3]
	global_load_dwordx4 v[144:147], v[14:15], off offset:-4096
	s_waitcnt lgkmcnt(0)
	v_mfma_f32_16x16x32_bf16 v[2:5], v[148:151], v[32:35], v[10:13]
	s_nop 2
	ds_read_b128 v[10:13], v165 offset:8192
	ds_read_b128 v[148:151], v180
	ds_read_b128 v[196:199], v167 offset:8192
	ds_read_b128 v[200:203], v181
	ds_read_b128 v[204:207], v176 offset:8192
	ds_read_b128 v[208:211], v182
	ds_read_b128 v[212:215], v178 offset:8192
	ds_read_b128 v[216:219], v183
	s_waitcnt lgkmcnt(7)
	v_mfma_f32_16x16x32_bf16 v[10:13], v[10:13], v[20:23], 0
	s_waitcnt lgkmcnt(6)
	v_mfma_f32_16x16x32_bf16 v[148:151], v[148:151], v[20:23], 0
	s_waitcnt lgkmcnt(5)
	v_mfma_f32_16x16x32_bf16 v[10:13], v[196:199], v[24:27], v[10:13]
	s_waitcnt lgkmcnt(4)
	v_mfma_f32_16x16x32_bf16 v[148:151], v[200:203], v[24:27], v[148:151]
	s_waitcnt lgkmcnt(3)
	v_mfma_f32_16x16x32_bf16 v[10:13], v[204:207], v[28:31], v[10:13]
	s_waitcnt lgkmcnt(2)
	v_mfma_f32_16x16x32_bf16 v[196:199], v[208:211], v[28:31], v[148:151]
	s_waitcnt lgkmcnt(1)
	v_mfma_f32_16x16x32_bf16 v[148:151], v[212:215], v[32:35], v[10:13]
	s_waitcnt lgkmcnt(0)
	v_mfma_f32_16x16x32_bf16 v[10:13], v[216:219], v[32:35], v[196:199]
	s_add_i32 s0, s11, 63
	v_cmp_gt_i32_e32 vcc, s0, v164
	v_cmp_le_i32_e64 s[0:1], s11, v184
	v_add_u32_e32 v205, s11, v187
	s_or_b64 s[14:15], vcc, s[0:1]
	v_add_u32_e32 v209, 2, v205
	v_add_u32_e32 v208, 3, v205
	v_add_u32_e32 v207, 4, v205
	v_add_u32_e32 v206, 5, v205
	v_add_u32_e32 v204, 6, v205
	v_add_u32_e32 v203, 7, v205
	v_add_u32_e32 v202, 32, v205
	v_add_u32_e32 v201, 34, v205
	v_add_u32_e32 v200, 35, v205
	v_add_u32_e32 v199, 36, v205
	v_add_u32_e32 v198, 37, v205
	v_add_u32_e32 v197, 38, v205
	v_add_u32_e32 v18, 39, v205
	s_and_saveexec_b64 s[26:27], s[14:15]
	s_xor_b64 s[26:27], exec, s[26:27]
	s_cbranch_execz .LBB0_1660
	v_cmp_gt_i32_e32 vcc, v205, v186
	v_cmp_le_i32_e64 s[0:1], v205, v185
	s_and_b64 s[16:17], vcc, s[0:1]
	v_cmp_ge_i32_e32 vcc, v205, v186
	v_cmp_lt_i32_e64 s[0:1], v205, v185
	s_and_b64 s[18:19], vcc, s[0:1]
	v_cmp_gt_i32_e32 vcc, v209, v186
	v_cmp_le_i32_e64 s[0:1], v209, v185
	s_and_b64 s[20:21], vcc, s[0:1]
	v_cmp_gt_i32_e32 vcc, v208, v186
	v_cmp_le_i32_e64 s[0:1], v208, v185
	s_and_b64 s[22:23], vcc, s[0:1]
	v_cmp_gt_i32_e32 vcc, v207, v186
	v_cmp_le_i32_e64 s[0:1], v207, v185
	s_and_b64 s[24:25], vcc, s[0:1]
	v_cmp_gt_i32_e32 vcc, v206, v186
	v_cmp_le_i32_e64 s[0:1], v206, v185
	s_and_b64 s[28:29], vcc, s[0:1]
	v_cmp_gt_i32_e32 vcc, v204, v186
	v_cmp_le_i32_e64 s[0:1], v204, v185
	s_and_b64 s[30:31], vcc, s[0:1]
	v_cmp_gt_i32_e32 vcc, v203, v186
	v_cmp_le_i32_e64 s[0:1], v203, v185
	s_and_b64 s[34:35], vcc, s[0:1]
	v_cmp_gt_i32_e32 vcc, v202, v186
	v_cmp_le_i32_e64 s[0:1], v202, v185
	s_and_b64 s[36:37], vcc, s[0:1]
	v_cmp_ge_i32_e32 vcc, v202, v186
	v_cmp_lt_i32_e64 s[0:1], v202, v185
	s_and_b64 s[38:39], vcc, s[0:1]
	v_cmp_gt_i32_e32 vcc, v201, v186
	v_cmp_le_i32_e64 s[0:1], v201, v185
	s_and_b64 s[40:41], vcc, s[0:1]
	v_cmp_gt_i32_e32 vcc, v200, v186
	v_cmp_le_i32_e64 s[0:1], v200, v185
	s_and_b64 s[42:43], vcc, s[0:1]
	v_cmp_gt_i32_e32 vcc, v199, v186
	v_cmp_le_i32_e64 s[0:1], v199, v185
	s_and_b64 s[44:45], vcc, s[0:1]
	v_cmp_gt_i32_e32 vcc, v198, v186
	v_cmp_le_i32_e64 s[0:1], v198, v185
	s_and_b64 s[46:47], vcc, s[0:1]
	v_cmp_gt_i32_e32 vcc, v197, v186
	v_cmp_le_i32_e64 s[0:1], v197, v185
	s_and_b64 s[48:49], vcc, s[0:1]
	v_cmp_gt_i32_e32 vcc, v18, v186
	v_cmp_le_i32_e64 s[0:1], v18, v185
	s_and_b64 s[0:1], vcc, s[0:1]
	v_cndmask_b32_e64 v6, v169, v6, s[16:17]
	v_cndmask_b32_e64 v7, v169, v7, s[18:19]
	v_cndmask_b32_e64 v8, v169, v8, s[20:21]
	v_cndmask_b32_e64 v9, v169, v9, s[22:23]
	v_cndmask_b32_e64 v2, v169, v2, s[24:25]
	v_cndmask_b32_e64 v3, v169, v3, s[28:29]
	v_cndmask_b32_e64 v4, v169, v4, s[30:31]
	v_cndmask_b32_e64 v5, v169, v5, s[34:35]
	v_cndmask_b32_e64 v148, v169, v148, s[36:37]
	v_cndmask_b32_e64 v149, v169, v149, s[38:39]
	v_cndmask_b32_e64 v150, v169, v150, s[40:41]
	v_cndmask_b32_e64 v151, v169, v151, s[42:43]
	v_cndmask_b32_e64 v10, v169, v10, s[44:45]
	v_cndmask_b32_e64 v11, v169, v11, s[46:47]
	v_cndmask_b32_e64 v12, v169, v12, s[48:49]
	v_cndmask_b32_e64 v13, v169, v13, s[0:1]

	.amdhsa_kernel _Z6k_mega6Params
		.amdhsa_group_segment_fixed_size 67088
		.amdhsa_private_segment_fixed_size 0
		.amdhsa_kernarg_size 440
		.amdhsa_user_sgpr_count 2
		.amdhsa_user_sgpr_dispatch_ptr 0
		.amdhsa_user_sgpr_queue_ptr 0
		.amdhsa_user_sgpr_kernarg_segment_ptr 1
		.amdhsa_user_sgpr_dispatch_id 0
		.amdhsa_user_sgpr_kernarg_preload_length 0
		.amdhsa_user_sgpr_kernarg_preload_offset 0
		.amdhsa_user_sgpr_private_segment_size 0
		.amdhsa_uses_dynamic_stack 0
		.amdhsa_enable_private_segment 0
		.amdhsa_system_sgpr_workgroup_id_x 1
		.amdhsa_system_sgpr_workgroup_id_y 0
		.amdhsa_system_sgpr_workgroup_id_z 0
		.amdhsa_system_sgpr_workgroup_info 0
		.amdhsa_system_vgpr_workitem_id 2
		.amdhsa_next_free_vgpr 255
		.amdhsa_next_free_sgpr 100
		.amdhsa_accum_offset 256
		.amdhsa_reserve_vcc 1
		.amdhsa_float_round_mode_32 0
		.amdhsa_float_round_mode_16_64 0
		.amdhsa_float_denorm_mode_32 3
		.amdhsa_float_denorm_mode_16_64 3
		.amdhsa_dx10_clamp 1
		.amdhsa_ieee_mode 1
		.amdhsa_fp16_overflow 0
		.amdhsa_tg_split 0
		.amdhsa_exception_fp_ieee_invalid_op 0
		.amdhsa_exception_fp_denorm_src 0
		.amdhsa_exception_fp_ieee_div_zero 0
		.amdhsa_exception_fp_ieee_overflow 0
		.amdhsa_exception_fp_ieee_underflow 0
		.amdhsa_exception_fp_ieee_inexact 0
		.amdhsa_exception_int_div_zero 0
	.end_amdhsa_kernel

amdhsa.kernels:
  - .agpr_count:     0
    .args:
      - .offset:         0
        .size:           184
        .value_kind:     by_value
      - .offset:         184
        .size:           4
        .value_kind:     hidden_block_count_x
      - .offset:         188
        .size:           4
        .value_kind:     hidden_block_count_y
      - .offset:         192
        .size:           4
        .value_kind:     hidden_block_count_z
      - .offset:         196
        .size:           2
        .value_kind:     hidden_group_size_x
      - .offset:         198
        .size:           2
        .value_kind:     hidden_group_size_y
      - .offset:         200
        .size:           2
        .value_kind:     hidden_group_size_z
      - .offset:         202
        .size:           2
        .value_kind:     hidden_remainder_x
      - .offset:         204
        .size:           2
        .value_kind:     hidden_remainder_y
      - .offset:         206
        .size:           2
        .value_kind:     hidden_remainder_z
      - .offset:         224
        .size:           8
        .value_kind:     hidden_global_offset_x
      - .offset:         232
        .size:           8
        .value_kind:     hidden_global_offset_y
      - .offset:         240
        .size:           8
        .value_kind:     hidden_global_offset_z
      - .offset:         248
        .size:           2
        .value_kind:     hidden_grid_dims
      - .offset:         272
        .size:           8
        .value_kind:     hidden_multigrid_sync_arg
    .group_segment_fixed_size: 67088
    .kernarg_segment_align: 8
    .kernarg_segment_size: 440
    .language:       OpenCL C
    .language_version:
      - 2
      - 0
    .max_flat_workgroup_size: 256
    .name:           _Z6k_mega6Params
    .private_segment_fixed_size: 0
    .sgpr_count:     106
    .sgpr_spill_count: 37
    .symbol:         _Z6k_mega6Params.kd
    .uniform_work_group_size: 1
    .uses_dynamic_stack: false
    .vgpr_count:     255
    .vgpr_spill_count: 0
    .wavefront_size: 64
